# v27 + prepass unit-count loops fast-forwarded + the one cooperative-groups grid sync replaced by the XCD barrier + attention QK LDS reads issued ahead of their MFMAs
# speedup vs baseline: 1.0031x; 1.0031x over previous
; __device__ __forceinline__ void xcd_barrier(const XcdBarrier& b, int tid_in) {
;     asm volatile("s_waitcnt vmcnt(0)" ::: "memory");
;     __syncthreads();
;     if (tid_in == 0) {
;         unsigned* bar = b.bar;
;         __builtin_amdgcn_s_waitcnt(0);
;         unsigned nloc = b.st[0], nx = b.st[1];
;         if (nloc == 0u) { xcd_barrier_complete(bar, b.x, nloc, nx); b.st[0] = nloc; b.st[1] = nx; }
; __global__ void __launch_bounds__(NTHR, 2) mega_fwd(Params P) {
;     ...
;         if (st > 2 * lo) { if (st == 2 * lo + 2) grid.sync(); else xcd_barrier(xbar, tid); }
.LBB0_33:
	s_cmp_le_i32 s26, s69
	s_cbranch_scc1 .LBB0_101
	v_readlane_b32 s0, v252, 21
	s_cmp_lg_u32 s26, s0
	s_mov_b64 s[36:37], -1
	s_waitcnt vmcnt(0)
	v_cmp_eq_u32_e32 vcc, 0, v246
	s_barrier
	s_and_saveexec_b64 s[36:37], vcc
	s_cbranch_execz .LBB0_87
	v_mov_b32_e32 v0, 0x24400
	s_waitcnt vmcnt(0) expcnt(0) lgkmcnt(0)
	ds_read_b32 v2, v0
	v_mov_b32_e32 v0, 0x24404
	ds_read_b32 v0, v0
	s_waitcnt lgkmcnt(1)
	v_cmp_ne_u32_e32 vcc, 0, v2
	s_cbranch_vccnz .LBB0_51
	s_mov_b32 s0, 1
	s_branch .LBB0_39

;     __host__ __device__ bool next(int i, Unit& u) const {
;         const long L = (long)i * G + c; if (L >= nwg) return false;
;     pg8::StaticOrder S; S.init(M, N, G, bid, rev, wgm); pg8::Unit u;
;     int nu = 0; while (S.next(nu, u)) ++nu;
.LBB0_116:
	s_ashr_i32 s90, s30, 31
	s_ashr_i32 s61, s60, 31
	s_sub_u32 s0, 0, s30
	s_subb_u32 s21, 0, s90
	s_mov_b32 s20, -1
	s_mov_b64 s[36:37], s[60:61]
	s_cmp_lg_u32 s30, 0x100
	s_cbranch_scc1 .Lff_0
	s_sub_i32 s24, 0x5ff, s60
	s_lshr_b32 s24, s24, 8
	s_add_i32 s20, s24, -1
	s_lshl_b32 s24, s24, 8
	s_add_u32 s36, s36, s24
	s_addc_u32 s37, s37, 0
.Lff_0:
	s_movk_i32 s3, 0xc1
	s_branch .LBB0_118

;     __host__ __device__ bool next(int i, Unit& u) const {
;         const long L = (long)i * G + c; if (L >= nwg) return false;
;     pg8::StaticOrder S; S.init(M, N, G, bid, rev, wgm); pg8::Unit u;
;     int nu = 0; while (S.next(nu, u)) ++nu;
.LBB0_399:
	s_and_b64 vcc, exec, s[36:37]
	s_cbranch_vccz .LBB0_456
	s_ashr_i32 s44, s30, 31
	s_ashr_i32 s61, s60, 31
	s_sub_u32 s20, 0, s30
	s_subb_u32 s21, 0, s44
	s_mov_b32 s0, -1
	s_mov_b64 s[36:37], s[60:61]
	s_cmp_lg_u32 s30, 0x100
	s_cbranch_scc1 .Lff_1
	s_sub_i32 s24, 0x47f, s60
	s_lshr_b32 s24, s24, 8
	s_add_i32 s0, s24, -1
	s_lshl_b32 s24, s24, 8
	s_add_u32 s36, s36, s24
	s_addc_u32 s37, s37, 0
.Lff_1:
	s_branch .LBB0_402
.LBB0_401:
	s_add_i32 s0, s0, 1
	s_add_u32 s36, s36, s30
	s_addc_u32 s37, s37, s44
	s_add_u32 s24, s20, s36
	s_addc_u32 s25, s21, s37
	v_mov_b64_e32 v[0:1], 0x480
	v_cmp_lt_i64_e32 vcc, s[24:25], v[0:1]
	s_cbranch_vccz .LBB0_404

;     pg8::StaticOrder S; S.init(M, N, G, bid, rev, wgm); pg8::Unit u;
;     int nu = 0; while (S.next(nu, u)) ++nu;
; __global__ void __launch_bounds__(NTHR, 2) mega_fwd(Params P) {
;     ...
;             const bool lazy = kind == 2 && f == 0 && l > 0, c2 = kind == 2 && f == 1 && l < DEPTH - 1;
;             if (lazy) rowscale_prepass(tab, PC, nullptr, T, D, 0, tid, bid, G, WGM_RES, nullptr, 1);
.LBB0_460:
	s_cmp_eq_u32 s63, 2
	v_readlane_b32 s8, v253, 55
	s_cselect_b64 s[20:21], -1, 0
	v_readlane_b32 s9, v253, 56
	s_mov_b64 s[44:45], s[20:21]
	s_and_b64 s[20:21], s[8:9], s[20:21]
	v_readlane_b32 s0, v254, 2
	s_cmp_gt_i32 s0, 0
	s_cselect_b64 s[22:23], -1, 0
	s_and_b64 s[78:79], s[20:21], s[22:23]
	s_andn2_b64 vcc, exec, s[78:79]
	s_cbranch_vccnz .LBB0_493
	s_ashr_i32 s0, s30, 31
	s_ashr_i32 s61, s60, 31
	s_sub_u32 s20, 0, s30
	s_subb_u32 s22, 0, s0
	s_mov_b32 s21, -1
	s_mov_b64 s[36:37], s[60:61]
	s_cmp_lg_u32 s30, 0x100
	s_cbranch_scc1 .Lff_2
	s_sub_i32 s24, 0x2ff, s60
	s_lshr_b32 s24, s24, 8
	s_add_i32 s21, s24, -1
	s_lshl_b32 s24, s24, 8
	s_add_u32 s36, s36, s24
	s_addc_u32 s37, s37, 0
.Lff_2:
	s_branch .LBB0_463
.LBB0_462:
	s_add_i32 s21, s21, 1
	s_add_u32 s36, s36, s30
	s_addc_u32 s37, s37, s0
	s_add_u32 s24, s20, s36
	s_addc_u32 s25, s22, s37
	v_cmp_lt_i64_e32 vcc, s[24:25], v[188:189]
	s_cbranch_vccz .LBB0_465

;     pg8::StaticOrder S; S.init(M, N, G, bid, rev, wgm); pg8::Unit u;
;     int nu = 0; while (S.next(nu, u)) ++nu;
; __global__ void __launch_bounds__(NTHR, 2) mega_fwd(Params P) {
;     ...
;         case 1: { if (f) rowscale_prepass(tab, PB, nullptr, T, 2 * FF, 0, tid, bid, G, WGM_FIN);
;                   else if (l == 0) rowscale_prepass(tab, nullptr, R2, T, 2 * FF, 0, tid, bid, G, WGM_FIN);
;                   else rowscale_prepass(tab, PC, nullptr, T, 2 * FF, 0, tid, bid, G, WGM_FIN, PB);
.LBB0_668:
	s_mov_b64 s[36:37], 0
	s_and_b64 vcc, exec, s[12:13]
	s_cbranch_vccz .LBB0_790
	s_add_u32 s20, s92, 0x300000
	s_addc_u32 s21, s93, 0
	v_writelane_b32 v253, s20, 46
	s_cmp_gt_i32 s63, 0
	s_mov_b64 s[38:39], -1
	v_writelane_b32 v253, s21, 47
	s_cbranch_scc0 .LBB0_788
	v_readlane_b32 s8, v253, 57
	v_readlane_b32 s9, v253, 58
	s_andn2_b64 vcc, exec, s[8:9]
	s_cbranch_vccnz .LBB0_703
	s_ashr_i32 s0, s30, 31
	s_ashr_i32 s61, s60, 31
	s_sub_u32 s20, 0, s30
	s_subb_u32 s22, 0, s0
	s_mov_b32 s21, -1
	s_mov_b64 s[36:37], s[60:61]
	s_cmp_lg_u32 s30, 0x100
	s_cbranch_scc1 .Lff_3
	s_sub_i32 s24, 0x107f, s60
	s_lshr_b32 s24, s24, 8
	s_add_i32 s21, s24, -1
	s_lshl_b32 s24, s24, 8
	s_add_u32 s36, s36, s24
	s_addc_u32 s37, s37, 0
.Lff_3:
	s_branch .LBB0_673
.LBB0_672:
	s_add_i32 s21, s21, 1
	s_add_u32 s36, s36, s30
	s_addc_u32 s37, s37, s0
	s_add_u32 s24, s20, s36
	s_addc_u32 s25, s22, s37
	v_cmp_lt_i64_e32 vcc, s[24:25], v[192:193]
	s_cbranch_vccz .LBB0_675

;     pg8::StaticOrder S; S.init(M, N, G, bid, rev, wgm); pg8::Unit u;
;     int nu = 0; while (S.next(nu, u)) ++nu;
; __global__ void __launch_bounds__(NTHR, 2) mega_fwd(Params P) {
;     ...
;         case 1: { if (f) rowscale_prepass(tab, PB, nullptr, T, 2 * FF, 0, tid, bid, G, WGM_FIN);
;                   else if (l == 0) rowscale_prepass(tab, nullptr, R2, T, 2 * FF, 0, tid, bid, G, WGM_FIN);
;                   else rowscale_prepass(tab, PC, nullptr, T, 2 * FF, 0, tid, bid, G, WGM_FIN, PB);
.LBB0_703:
	s_mov_b64 s[36:37], 0x1080000
	s_and_b64 vcc, exec, s[38:39]
	s_cbranch_vccz .LBB0_771
	v_readlane_b32 s0, v254, 2
	s_cmp_lg_u32 s0, 0
	s_cbranch_scc0 .LBB0_737
	s_ashr_i32 s0, s30, 31
	s_ashr_i32 s61, s60, 31
	s_sub_u32 s20, 0, s30
	s_subb_u32 s22, 0, s0
	s_mov_b32 s21, -1
	s_mov_b64 s[36:37], s[60:61]
	s_cmp_lg_u32 s30, 0x100
	s_cbranch_scc1 .Lff_4
	s_sub_i32 s24, 0x107f, s60
	s_lshr_b32 s24, s24, 8
	s_add_i32 s21, s24, -1
	s_lshl_b32 s24, s24, 8
	s_add_u32 s36, s36, s24
	s_addc_u32 s37, s37, 0
.Lff_4:
	s_branch .LBB0_707
.LBB0_706:
	s_add_i32 s21, s21, 1
	s_add_u32 s36, s36, s30
	s_addc_u32 s37, s37, s0
	s_add_u32 s24, s20, s36
	s_addc_u32 s25, s22, s37
	v_cmp_lt_i64_e32 vcc, s[24:25], v[192:193]
	s_cbranch_vccz .LBB0_709

;     pg8::StaticOrder S; S.init(M, N, G, bid, rev, wgm); pg8::Unit u;
;     int nu = 0; while (S.next(nu, u)) ++nu;
; __global__ void __launch_bounds__(NTHR, 2) mega_fwd(Params P) {
;     ...
;         case 1: { if (f) rowscale_prepass(tab, PB, nullptr, T, 2 * FF, 0, tid, bid, G, WGM_FIN);
;                   else if (l == 0) rowscale_prepass(tab, nullptr, R2, T, 2 * FF, 0, tid, bid, G, WGM_FIN);
;                   else rowscale_prepass(tab, PC, nullptr, T, 2 * FF, 0, tid, bid, G, WGM_FIN, PB);
.LBB0_737:
	s_cbranch_execz .LBB0_770
	s_ashr_i32 s0, s30, 31
	s_ashr_i32 s61, s60, 31
	s_sub_u32 s20, 0, s30
	s_subb_u32 s22, 0, s0
	s_mov_b32 s21, -1
	s_mov_b64 s[36:37], s[60:61]
	s_cmp_lg_u32 s30, 0x100
	s_cbranch_scc1 .Lff_5
	s_sub_i32 s24, 0x107f, s60
	s_lshr_b32 s24, s24, 8
	s_add_i32 s21, s24, -1
	s_lshl_b32 s24, s24, 8
	s_add_u32 s36, s36, s24
	s_addc_u32 s37, s37, 0
.Lff_5:
	s_branch .LBB0_740
.LBB0_739:
	s_add_i32 s21, s21, 1
	s_add_u32 s36, s36, s30
	s_addc_u32 s37, s37, s0
	s_add_u32 s24, s20, s36
	s_addc_u32 s25, s22, s37
	v_cmp_lt_i64_e32 vcc, s[24:25], v[192:193]
	s_cbranch_vccz .LBB0_742
